# P5/P6/P7 epilogues: loads hoisted, counted waits, global_* instead of flat_*
# baseline (speedup 1.0000x reference)
; __device__ __forceinline__ u32x4 pack8(const f32x4& v0, const f32x4& v1) { u32x4 w; w.x = cvt_pk_bf16(v0[0], v0[1]); w.y = cvt_pk_bf16(v0[2], v0[3]); w.z = cvt_pk_bf16(v1[0], v1[1]); w.w = cvt_pk_bf16(v1[2], v1[3]); return w; }
; #define EPI_LOOP_ROWS _Pragma("unroll") for (int ai = 0; ai < 2; ++ai) _Pragma("unroll") for (int m = 0; m < 4; ++m)
; #define EPI_LOOP_BJ _Pragma("unroll") for (int bj = 0; bj < 2; ++bj)
;     __device__ __forceinline__ void operator()(const f32x4 (&acc)[2][2][4][2], const Unit& u, int wr, int wc, int fr, int fq) const {
;         const int col0 = u.pn * BM + wc * 32 + 8 * fq, row0 = u.pm * BM + wr * 64 + fr;
;         EPI_LOOP_ROWS { const int row = row0 + ai * HALF + m * 16; const float rs = __builtin_amdgcn_rsqf(ss[row] * (1.f / 2048.f) + 1e-6f);
;             EPI_LOOP_BJ { f32x4 v0 = acc[ai][bj][m][0] * rs, v1 = acc[ai][bj][m][1] * rs;
; #pragma unroll
;                 for (int i = 0; i < 4; ++i) { const float a = fmaxf(v0[i], 0.f), b = fmaxf(v1[i], 0.f); v0[i] = a * a; v1[i] = b * b; }
;                 *(u32x4*)(H + (size_t)row * 8192 + col0 + bj * HALF) = pack8(v0, v1); } }
;     }
.LBB0_832:
	v_lshl_add_u32 v148, s0, 8, v152
	v_ashrrev_i32_e32 v149, 31, v148
	v_lshl_add_u64 v[146:147], v[148:149], 2, s[8:9]
	global_load_dword v150, v[146:147], off
	global_load_dword v232, v[146:147], off offset:64
	global_load_dword v233, v[146:147], off offset:128
	global_load_dword v234, v[146:147], off offset:192
	global_load_dword v235, v[146:147], off offset:512
	global_load_dword v236, v[146:147], off offset:576
	global_load_dword v237, v[146:147], off offset:640
	global_load_dword v238, v[146:147], off offset:704
	v_lshlrev_b64 v[160:161], 14, v[148:149]
	v_lshl_or_b32 v144, s1, 8, v154
	v_ashrrev_i32_e32 v145, 31, v144
	s_waitcnt vmcnt(0)
	v_fmamk_f32 v149, v150, 0x3a000000, v158
	v_rsq_f32_e32 v162, v149
	v_lshlrev_b64 v[150:151], 1, v[144:145]
	v_lshl_add_u64 v[144:145], s[12:13], 0, v[160:161]
	v_lshl_add_u64 v[144:145], v[144:145], 0, v[150:151]
	v_pk_mul_f32 v[122:123], v[122:123], v[162:163] op_sel_hi:[1,0]
	v_pk_mul_f32 v[120:121], v[120:121], v[162:163] op_sel_hi:[1,0]
	v_pk_mul_f32 v[126:127], v[126:127], v[162:163] op_sel_hi:[1,0]
	v_pk_mul_f32 v[124:125], v[124:125], v[162:163] op_sel_hi:[1,0]
	v_pk_mul_f32 v[114:115], v[114:115], v[162:163] op_sel_hi:[1,0]
	v_pk_mul_f32 v[112:113], v[112:113], v[162:163] op_sel_hi:[1,0]
	v_pk_mul_f32 v[118:119], v[118:119], v[162:163] op_sel_hi:[1,0]
	v_pk_mul_f32 v[116:117], v[116:117], v[162:163] op_sel_hi:[1,0]
	v_max_f32_e32 v120, 0, v120
	v_max_f32_e32 v124, 0, v124
	v_max_f32_e32 v121, 0, v121
	v_max_f32_e32 v125, 0, v125
	v_max_f32_e32 v122, 0, v122
	v_max_f32_e32 v126, 0, v126
	v_max_f32_e32 v123, 0, v123
	v_max_f32_e32 v127, 0, v127
	v_max_f32_e32 v112, 0, v112
	v_max_f32_e32 v113, 0, v113
	v_max_f32_e32 v114, 0, v114
	v_max_f32_e32 v115, 0, v115
	v_max_f32_e32 v116, 0, v116
	v_max_f32_e32 v117, 0, v117
	v_max_f32_e32 v118, 0, v118
	v_max_f32_e32 v119, 0, v119
	v_mul_f32_e32 v120, v120, v120
	v_mul_f32_e32 v124, v124, v124
	v_mul_f32_e32 v121, v121, v121
	v_mul_f32_e32 v125, v125, v125
	v_mul_f32_e32 v122, v122, v122
	v_mul_f32_e32 v126, v126, v126
	v_mul_f32_e32 v123, v123, v123
	v_mul_f32_e32 v127, v127, v127
	v_mul_f32_e32 v149, v112, v112
	v_mul_f32_e32 v159, v113, v113
	v_mul_f32_e32 v160, v114, v114
	v_mul_f32_e32 v161, v115, v115
	v_cvt_pk_bf16_f32 v112, v120, v121
	v_cvt_pk_bf16_f32 v113, v122, v123
	v_cvt_pk_bf16_f32 v114, v124, v125
	v_cvt_pk_bf16_f32 v115, v126, v127
	v_mul_f32_e32 v116, v116, v116
	v_mul_f32_e32 v117, v117, v117
	v_mul_f32_e32 v118, v118, v118
	v_mul_f32_e32 v119, v119, v119
	global_store_dwordx4 v[144:145], v[112:115], off
	s_nop 1
	v_cvt_pk_bf16_f32 v112, v116, v117
	v_cvt_pk_bf16_f32 v113, v118, v119
	v_cvt_pk_bf16_f32 v114, v149, v159
	v_cvt_pk_bf16_f32 v115, v160, v161
	global_store_dwordx4 v[144:145], v[112:115], off offset:256
	s_nop 1
	v_mov_b32_e32 v114, v232
	s_nop 0
	v_or_b32_e32 v112, 16, v148
	v_ashrrev_i32_e32 v113, 31, v112
	v_lshlrev_b64 v[112:113], 14, v[112:113]
	v_lshl_add_u64 v[112:113], s[12:13], 0, v[112:113]
	v_lshl_add_u64 v[112:113], v[112:113], 0, v[150:151]
	v_fmamk_f32 v114, v114, 0x3a000000, v158
	v_rsq_f32_e32 v114, v114
	s_nop 0
	v_pk_mul_f32 v[110:111], v[110:111], v[114:115] op_sel_hi:[1,0]
	v_pk_mul_f32 v[108:109], v[108:109], v[114:115] op_sel_hi:[1,0]
	v_pk_mul_f32 v[106:107], v[106:107], v[114:115] op_sel_hi:[1,0]
	v_pk_mul_f32 v[104:105], v[104:105], v[114:115] op_sel_hi:[1,0]
	v_pk_mul_f32 v[98:99], v[98:99], v[114:115] op_sel_hi:[1,0]
	v_pk_mul_f32 v[96:97], v[96:97], v[114:115] op_sel_hi:[1,0]
	v_pk_mul_f32 v[102:103], v[102:103], v[114:115] op_sel_hi:[1,0]
	v_pk_mul_f32 v[100:101], v[100:101], v[114:115] op_sel_hi:[1,0]
	v_max_f32_e32 v108, 0, v108
	v_max_f32_e32 v104, 0, v104
	v_max_f32_e32 v109, 0, v109
	v_max_f32_e32 v105, 0, v105
	v_max_f32_e32 v110, 0, v110
	v_max_f32_e32 v106, 0, v106
	v_max_f32_e32 v111, 0, v111
	v_max_f32_e32 v107, 0, v107
	v_max_f32_e32 v96, 0, v96
	v_max_f32_e32 v97, 0, v97
	v_max_f32_e32 v98, 0, v98
	v_max_f32_e32 v99, 0, v99
	v_max_f32_e32 v100, 0, v100
	v_max_f32_e32 v101, 0, v101
	v_max_f32_e32 v102, 0, v102
	v_max_f32_e32 v103, 0, v103
	v_mul_f32_e32 v108, v108, v108
	v_mul_f32_e32 v104, v104, v104
	v_mul_f32_e32 v109, v109, v109
	v_mul_f32_e32 v105, v105, v105
	v_mul_f32_e32 v110, v110, v110
	v_mul_f32_e32 v106, v106, v106
	v_mul_f32_e32 v111, v111, v111
	v_mul_f32_e32 v107, v107, v107
	v_mul_f32_e32 v114, v96, v96
	v_mul_f32_e32 v115, v97, v97
	v_mul_f32_e32 v116, v98, v98
	v_mul_f32_e32 v117, v99, v99
	v_cvt_pk_bf16_f32 v96, v108, v109
	v_cvt_pk_bf16_f32 v97, v110, v111
	v_cvt_pk_bf16_f32 v98, v104, v105
	v_cvt_pk_bf16_f32 v99, v106, v107
	v_mul_f32_e32 v100, v100, v100
	v_mul_f32_e32 v101, v101, v101
	v_mul_f32_e32 v102, v102, v102
	v_mul_f32_e32 v103, v103, v103
	global_store_dwordx4 v[112:113], v[96:99], off
	s_nop 1
	v_cvt_pk_bf16_f32 v96, v100, v101
	v_cvt_pk_bf16_f32 v97, v102, v103
	v_cvt_pk_bf16_f32 v98, v114, v115
	v_cvt_pk_bf16_f32 v99, v116, v117
	global_store_dwordx4 v[112:113], v[96:99], off offset:256
	s_nop 1
	v_mov_b32_e32 v98, v233
	s_nop 0
	v_or_b32_e32 v96, 32, v148
	v_ashrrev_i32_e32 v97, 31, v96
	v_lshlrev_b64 v[96:97], 14, v[96:97]
	v_lshl_add_u64 v[96:97], s[12:13], 0, v[96:97]
	v_lshl_add_u64 v[96:97], v[96:97], 0, v[150:151]
	v_fmamk_f32 v98, v98, 0x3a000000, v158
	v_rsq_f32_e32 v98, v98
	s_nop 0
	v_pk_mul_f32 v[94:95], v[94:95], v[98:99] op_sel_hi:[1,0]
	v_pk_mul_f32 v[92:93], v[92:93], v[98:99] op_sel_hi:[1,0]
	v_pk_mul_f32 v[90:91], v[90:91], v[98:99] op_sel_hi:[1,0]
	v_pk_mul_f32 v[88:89], v[88:89], v[98:99] op_sel_hi:[1,0]
	v_pk_mul_f32 v[82:83], v[82:83], v[98:99] op_sel_hi:[1,0]
	v_pk_mul_f32 v[80:81], v[80:81], v[98:99] op_sel_hi:[1,0]
; __device__ __forceinline__ u32x4 pack8(const f32x4& v0, const f32x4& v1) { u32x4 w; w.x = cvt_pk_bf16(v0[0], v0[1]); w.y = cvt_pk_bf16(v0[2], v0[3]); w.z = cvt_pk_bf16(v1[0], v1[1]); w.w = cvt_pk_bf16(v1[2], v1[3]); return w; }
; #define EPI_LOOP_ROWS _Pragma("unroll") for (int ai = 0; ai < 2; ++ai) _Pragma("unroll") for (int m = 0; m < 4; ++m)
; #define EPI_LOOP_BJ _Pragma("unroll") for (int bj = 0; bj < 2; ++bj)
;     __device__ __forceinline__ void operator()(const f32x4 (&acc)[2][2][4][2], const Unit& u, int wr, int wc, int fr, int fq) const {
;     ...
;         EPI_LOOP_ROWS { const int row = row0 + ai * HALF + m * 16; const float rs = __builtin_amdgcn_rsqf(ss[row] * (1.f / 2048.f) + 1e-6f);
;             EPI_LOOP_BJ { f32x4 v0 = acc[ai][bj][m][0] * rs, v1 = acc[ai][bj][m][1] * rs;
; #pragma unroll
;                 for (int i = 0; i < 4; ++i) { const float a = fmaxf(v0[i], 0.f), b = fmaxf(v1[i], 0.f); v0[i] = a * a; v1[i] = b * b; }
;                 *(u32x4*)(H + (size_t)row * 8192 + col0 + bj * HALF) = pack8(v0, v1); } }
	v_pk_mul_f32 v[86:87], v[86:87], v[98:99] op_sel_hi:[1,0]
	v_pk_mul_f32 v[84:85], v[84:85], v[98:99] op_sel_hi:[1,0]
	v_max_f32_e32 v92, 0, v92
	v_max_f32_e32 v88, 0, v88
	v_max_f32_e32 v93, 0, v93
	v_max_f32_e32 v89, 0, v89
	v_max_f32_e32 v94, 0, v94
	v_max_f32_e32 v90, 0, v90
	v_max_f32_e32 v95, 0, v95
	v_max_f32_e32 v91, 0, v91
	v_max_f32_e32 v80, 0, v80
	v_max_f32_e32 v81, 0, v81
	v_max_f32_e32 v82, 0, v82
	v_max_f32_e32 v83, 0, v83
	v_max_f32_e32 v84, 0, v84
	v_max_f32_e32 v85, 0, v85
	v_max_f32_e32 v86, 0, v86
	v_max_f32_e32 v87, 0, v87
	v_mul_f32_e32 v92, v92, v92
	v_mul_f32_e32 v88, v88, v88
	v_mul_f32_e32 v93, v93, v93
	v_mul_f32_e32 v89, v89, v89
	v_mul_f32_e32 v94, v94, v94
	v_mul_f32_e32 v90, v90, v90
	v_mul_f32_e32 v95, v95, v95
	v_mul_f32_e32 v91, v91, v91
	v_mul_f32_e32 v98, v80, v80
	v_mul_f32_e32 v99, v81, v81
	v_mul_f32_e32 v100, v82, v82
	v_mul_f32_e32 v101, v83, v83
	v_cvt_pk_bf16_f32 v80, v92, v93
	v_cvt_pk_bf16_f32 v81, v94, v95
	v_cvt_pk_bf16_f32 v82, v88, v89
	v_cvt_pk_bf16_f32 v83, v90, v91
	v_mul_f32_e32 v84, v84, v84
	v_mul_f32_e32 v85, v85, v85
	v_mul_f32_e32 v86, v86, v86
	v_mul_f32_e32 v87, v87, v87
	global_store_dwordx4 v[96:97], v[80:83], off
	s_nop 1
	v_cvt_pk_bf16_f32 v80, v84, v85
	v_cvt_pk_bf16_f32 v81, v86, v87
	v_cvt_pk_bf16_f32 v82, v98, v99
	v_cvt_pk_bf16_f32 v83, v100, v101
	global_store_dwordx4 v[96:97], v[80:83], off offset:256
	s_nop 1
	v_mov_b32_e32 v82, v234
	s_nop 0
	v_or_b32_e32 v80, 48, v148
	v_ashrrev_i32_e32 v81, 31, v80
	v_lshlrev_b64 v[80:81], 14, v[80:81]
	v_lshl_add_u64 v[80:81], s[12:13], 0, v[80:81]
	v_lshl_add_u64 v[80:81], v[80:81], 0, v[150:151]
	v_fmamk_f32 v82, v82, 0x3a000000, v158
	v_rsq_f32_e32 v82, v82
	s_nop 0
	v_pk_mul_f32 v[78:79], v[78:79], v[82:83] op_sel_hi:[1,0]
	v_pk_mul_f32 v[76:77], v[76:77], v[82:83] op_sel_hi:[1,0]
	v_pk_mul_f32 v[74:75], v[74:75], v[82:83] op_sel_hi:[1,0]
	v_pk_mul_f32 v[72:73], v[72:73], v[82:83] op_sel_hi:[1,0]
	v_pk_mul_f32 v[66:67], v[66:67], v[82:83] op_sel_hi:[1,0]
	v_pk_mul_f32 v[64:65], v[64:65], v[82:83] op_sel_hi:[1,0]
	v_pk_mul_f32 v[70:71], v[70:71], v[82:83] op_sel_hi:[1,0]
	v_pk_mul_f32 v[68:69], v[68:69], v[82:83] op_sel_hi:[1,0]
	v_max_f32_e32 v76, 0, v76
	v_max_f32_e32 v72, 0, v72
	v_max_f32_e32 v77, 0, v77
	v_max_f32_e32 v73, 0, v73
	v_max_f32_e32 v78, 0, v78
	v_max_f32_e32 v74, 0, v74
	v_max_f32_e32 v79, 0, v79
	v_max_f32_e32 v75, 0, v75
	v_max_f32_e32 v64, 0, v64
	v_max_f32_e32 v65, 0, v65
	v_max_f32_e32 v66, 0, v66
	v_max_f32_e32 v67, 0, v67
	v_max_f32_e32 v68, 0, v68
	v_max_f32_e32 v69, 0, v69
	v_max_f32_e32 v70, 0, v70
	v_max_f32_e32 v71, 0, v71
	v_mul_f32_e32 v76, v76, v76
	v_mul_f32_e32 v72, v72, v72
	v_mul_f32_e32 v77, v77, v77
	v_mul_f32_e32 v73, v73, v73
	v_mul_f32_e32 v78, v78, v78
	v_mul_f32_e32 v74, v74, v74
	v_mul_f32_e32 v79, v79, v79
	v_mul_f32_e32 v75, v75, v75
	v_mul_f32_e32 v82, v64, v64
	v_mul_f32_e32 v83, v65, v65
	v_mul_f32_e32 v84, v66, v66
	v_mul_f32_e32 v85, v67, v67
	v_cvt_pk_bf16_f32 v64, v76, v77
	v_cvt_pk_bf16_f32 v65, v78, v79
	v_cvt_pk_bf16_f32 v66, v72, v73
	v_cvt_pk_bf16_f32 v67, v74, v75
	v_mul_f32_e32 v68, v68, v68
	v_mul_f32_e32 v69, v69, v69
	v_mul_f32_e32 v70, v70, v70
	v_mul_f32_e32 v71, v71, v71
	global_store_dwordx4 v[80:81], v[64:67], off
	s_nop 1
	v_cvt_pk_bf16_f32 v64, v68, v69
	v_cvt_pk_bf16_f32 v65, v70, v71
	v_cvt_pk_bf16_f32 v66, v82, v83
	v_cvt_pk_bf16_f32 v67, v84, v85
	global_store_dwordx4 v[80:81], v[64:67], off offset:256
	s_nop 1
	v_mov_b32_e32 v66, v235
	v_add_co_u32_e32 v68, vcc, s63, v144
	v_lshl_add_u64 v[64:65], v[144:145], 0, s[22:23]
	s_nop 0
	v_addc_co_u32_e32 v69, vcc, 0, v145, vcc
	v_fmamk_f32 v66, v66, 0x3a000000, v158
	v_rsq_f32_e32 v66, v66
	s_nop 0
	v_pk_mul_f32 v[62:63], v[62:63], v[66:67] op_sel_hi:[1,0]
	v_pk_mul_f32 v[60:61], v[60:61], v[66:67] op_sel_hi:[1,0]
	v_pk_mul_f32 v[58:59], v[58:59], v[66:67] op_sel_hi:[1,0]
	v_pk_mul_f32 v[56:57], v[56:57], v[66:67] op_sel_hi:[1,0]
	v_pk_mul_f32 v[50:51], v[50:51], v[66:67] op_sel_hi:[1,0]
	v_pk_mul_f32 v[48:49], v[48:49], v[66:67] op_sel_hi:[1,0]
	v_pk_mul_f32 v[54:55], v[54:55], v[66:67] op_sel_hi:[1,0]
	v_pk_mul_f32 v[52:53], v[52:53], v[66:67] op_sel_hi:[1,0]
	v_max_f32_e32 v60, 0, v60
	v_max_f32_e32 v56, 0, v56
	v_max_f32_e32 v61, 0, v61
	v_max_f32_e32 v57, 0, v57
	v_max_f32_e32 v62, 0, v62
	v_max_f32_e32 v58, 0, v58
	v_max_f32_e32 v63, 0, v63
	v_max_f32_e32 v59, 0, v59
	v_max_f32_e32 v48, 0, v48
	v_max_f32_e32 v49, 0, v49
	v_max_f32_e32 v50, 0, v50
	v_max_f32_e32 v51, 0, v51
	v_max_f32_e32 v52, 0, v52
	v_max_f32_e32 v53, 0, v53
	v_max_f32_e32 v54, 0, v54
	v_max_f32_e32 v55, 0, v55
	v_mul_f32_e32 v60, v60, v60
	v_mul_f32_e32 v56, v56, v56
	v_mul_f32_e32 v61, v61, v61
	v_mul_f32_e32 v57, v57, v57
	v_mul_f32_e32 v62, v62, v62
	v_mul_f32_e32 v58, v58, v58
	v_mul_f32_e32 v63, v63, v63
	v_mul_f32_e32 v59, v59, v59
	v_mul_f32_e32 v66, v48, v48
	v_mul_f32_e32 v67, v49, v49
	v_mul_f32_e32 v70, v50, v50
	v_mul_f32_e32 v71, v51, v51
	v_cvt_pk_bf16_f32 v48, v60, v61
	v_cvt_pk_bf16_f32 v49, v62, v63
	v_cvt_pk_bf16_f32 v50, v56, v57
	v_cvt_pk_bf16_f32 v51, v58, v59
	v_mul_f32_e32 v52, v52, v52
	v_mul_f32_e32 v53, v53, v53
	v_mul_f32_e32 v54, v54, v54
	v_mul_f32_e32 v55, v55, v55
	global_store_dwordx4 v[68:69], v[48:51], off
	s_nop 1
	v_cvt_pk_bf16_f32 v48, v52, v53
	v_cvt_pk_bf16_f32 v49, v54, v55
	v_cvt_pk_bf16_f32 v50, v66, v67
	v_cvt_pk_bf16_f32 v51, v70, v71
	global_store_dwordx4 v[64:65], v[48:51], off offset:256
	s_nop 1
	v_mov_b32_e32 v50, v236
	v_add_co_u32_e32 v52, vcc, s64, v144
	v_lshl_add_u64 v[48:49], v[144:145], 0, s[24:25]
	s_nop 0
	v_addc_co_u32_e32 v53, vcc, 0, v145, vcc
	v_fmamk_f32 v50, v50, 0x3a000000, v158
; __device__ __forceinline__ u32x4 pack8(const f32x4& v0, const f32x4& v1) { u32x4 w; w.x = cvt_pk_bf16(v0[0], v0[1]); w.y = cvt_pk_bf16(v0[2], v0[3]); w.z = cvt_pk_bf16(v1[0], v1[1]); w.w = cvt_pk_bf16(v1[2], v1[3]); return w; }
; #define EPI_LOOP_ROWS _Pragma("unroll") for (int ai = 0; ai < 2; ++ai) _Pragma("unroll") for (int m = 0; m < 4; ++m)
; #define EPI_LOOP_BJ _Pragma("unroll") for (int bj = 0; bj < 2; ++bj)
;     __device__ __forceinline__ void operator()(const f32x4 (&acc)[2][2][4][2], const Unit& u, int wr, int wc, int fr, int fq) const {
;     ...
;         EPI_LOOP_ROWS { const int row = row0 + ai * HALF + m * 16; const float rs = __builtin_amdgcn_rsqf(ss[row] * (1.f / 2048.f) + 1e-6f);
;             EPI_LOOP_BJ { f32x4 v0 = acc[ai][bj][m][0] * rs, v1 = acc[ai][bj][m][1] * rs;
; #pragma unroll
;                 for (int i = 0; i < 4; ++i) { const float a = fmaxf(v0[i], 0.f), b = fmaxf(v1[i], 0.f); v0[i] = a * a; v1[i] = b * b; }
;                 *(u32x4*)(H + (size_t)row * 8192 + col0 + bj * HALF) = pack8(v0, v1); } }
;     }
	v_rsq_f32_e32 v50, v50
	s_nop 0
	v_pk_mul_f32 v[46:47], v[46:47], v[50:51] op_sel_hi:[1,0]
	v_pk_mul_f32 v[44:45], v[44:45], v[50:51] op_sel_hi:[1,0]
	v_pk_mul_f32 v[42:43], v[42:43], v[50:51] op_sel_hi:[1,0]
	v_pk_mul_f32 v[40:41], v[40:41], v[50:51] op_sel_hi:[1,0]
	v_pk_mul_f32 v[34:35], v[34:35], v[50:51] op_sel_hi:[1,0]
	v_pk_mul_f32 v[32:33], v[32:33], v[50:51] op_sel_hi:[1,0]
	v_pk_mul_f32 v[38:39], v[38:39], v[50:51] op_sel_hi:[1,0]
	v_pk_mul_f32 v[36:37], v[36:37], v[50:51] op_sel_hi:[1,0]
	v_max_f32_e32 v44, 0, v44
	v_max_f32_e32 v40, 0, v40
	v_max_f32_e32 v45, 0, v45
	v_max_f32_e32 v41, 0, v41
	v_max_f32_e32 v46, 0, v46
	v_max_f32_e32 v42, 0, v42
	v_max_f32_e32 v47, 0, v47
	v_max_f32_e32 v43, 0, v43
	v_max_f32_e32 v32, 0, v32
	v_max_f32_e32 v33, 0, v33
	v_max_f32_e32 v34, 0, v34
	v_max_f32_e32 v35, 0, v35
	v_max_f32_e32 v36, 0, v36
	v_max_f32_e32 v37, 0, v37
	v_max_f32_e32 v38, 0, v38
	v_max_f32_e32 v39, 0, v39
	v_mul_f32_e32 v44, v44, v44
	v_mul_f32_e32 v40, v40, v40
	v_mul_f32_e32 v45, v45, v45
	v_mul_f32_e32 v41, v41, v41
	v_mul_f32_e32 v46, v46, v46
	v_mul_f32_e32 v42, v42, v42
	v_mul_f32_e32 v47, v47, v47
	v_mul_f32_e32 v43, v43, v43
	v_mul_f32_e32 v50, v32, v32
	v_mul_f32_e32 v51, v33, v33
	v_mul_f32_e32 v54, v34, v34
	v_mul_f32_e32 v55, v35, v35
	v_cvt_pk_bf16_f32 v32, v44, v45
	v_cvt_pk_bf16_f32 v33, v46, v47
	v_cvt_pk_bf16_f32 v34, v40, v41
	v_cvt_pk_bf16_f32 v35, v42, v43
	v_mul_f32_e32 v36, v36, v36
	v_mul_f32_e32 v37, v37, v37
	v_mul_f32_e32 v38, v38, v38
	v_mul_f32_e32 v39, v39, v39
	global_store_dwordx4 v[52:53], v[32:35], off
	s_nop 1
	v_cvt_pk_bf16_f32 v32, v36, v37
	v_cvt_pk_bf16_f32 v33, v38, v39
	v_cvt_pk_bf16_f32 v34, v50, v51
	v_cvt_pk_bf16_f32 v35, v54, v55
	global_store_dwordx4 v[48:49], v[32:35], off offset:256
	s_nop 1
	v_mov_b32_e32 v34, v237
	v_add_co_u32_e32 v36, vcc, s65, v144
	v_lshl_add_u64 v[32:33], v[144:145], 0, s[26:27]
	s_nop 0
	v_addc_co_u32_e32 v37, vcc, 0, v145, vcc
	s_andn2_b64 vcc, exec, s[6:7]
	v_fmamk_f32 v34, v34, 0x3a000000, v158
	v_rsq_f32_e32 v34, v34
	s_nop 0
	v_pk_mul_f32 v[30:31], v[30:31], v[34:35] op_sel_hi:[1,0]
	v_pk_mul_f32 v[28:29], v[28:29], v[34:35] op_sel_hi:[1,0]
	v_pk_mul_f32 v[26:27], v[26:27], v[34:35] op_sel_hi:[1,0]
	v_pk_mul_f32 v[24:25], v[24:25], v[34:35] op_sel_hi:[1,0]
	v_pk_mul_f32 v[18:19], v[18:19], v[34:35] op_sel_hi:[1,0]
	v_pk_mul_f32 v[16:17], v[16:17], v[34:35] op_sel_hi:[1,0]
	v_pk_mul_f32 v[22:23], v[22:23], v[34:35] op_sel_hi:[1,0]
	v_pk_mul_f32 v[20:21], v[20:21], v[34:35] op_sel_hi:[1,0]
	v_max_f32_e32 v28, 0, v28
	v_max_f32_e32 v24, 0, v24
	v_max_f32_e32 v29, 0, v29
	v_max_f32_e32 v25, 0, v25
	v_max_f32_e32 v30, 0, v30
	v_max_f32_e32 v26, 0, v26
	v_max_f32_e32 v31, 0, v31
	v_max_f32_e32 v27, 0, v27
	v_max_f32_e32 v16, 0, v16
	v_max_f32_e32 v17, 0, v17
	v_max_f32_e32 v18, 0, v18
	v_max_f32_e32 v19, 0, v19
	v_max_f32_e32 v20, 0, v20
	v_max_f32_e32 v21, 0, v21
	v_max_f32_e32 v22, 0, v22
	v_max_f32_e32 v23, 0, v23
	v_mul_f32_e32 v28, v28, v28
	v_mul_f32_e32 v24, v24, v24
	v_mul_f32_e32 v29, v29, v29
	v_mul_f32_e32 v25, v25, v25
	v_mul_f32_e32 v30, v30, v30
	v_mul_f32_e32 v26, v26, v26
	v_mul_f32_e32 v31, v31, v31
	v_mul_f32_e32 v27, v27, v27
	v_mul_f32_e32 v34, v16, v16
	v_mul_f32_e32 v35, v17, v17
	v_mul_f32_e32 v38, v18, v18
	v_mul_f32_e32 v39, v19, v19
	v_cvt_pk_bf16_f32 v16, v28, v29
	v_cvt_pk_bf16_f32 v17, v30, v31
	v_cvt_pk_bf16_f32 v18, v24, v25
	v_cvt_pk_bf16_f32 v19, v26, v27
	v_mul_f32_e32 v20, v20, v20
	v_mul_f32_e32 v21, v21, v21
	v_mul_f32_e32 v22, v22, v22
	v_mul_f32_e32 v23, v23, v23
	global_store_dwordx4 v[36:37], v[16:19], off
	s_nop 1
	v_cvt_pk_bf16_f32 v16, v20, v21
	v_cvt_pk_bf16_f32 v17, v22, v23
	v_cvt_pk_bf16_f32 v18, v34, v35
	v_cvt_pk_bf16_f32 v19, v38, v39
	global_store_dwordx4 v[32:33], v[16:19], off offset:256
	s_nop 1
	v_mov_b32_e32 v18, v238
	v_add_co_u32_e64 v20, s[0:1], s66, v144
	v_lshl_add_u64 v[16:17], v[144:145], 0, s[28:29]
	s_nop 0
	v_addc_co_u32_e64 v21, s[0:1], 0, v145, s[0:1]
	s_mov_b64 s[0:1], -1
	v_fmamk_f32 v18, v18, 0x3a000000, v158
	v_rsq_f32_e32 v18, v18
	s_nop 0
	v_pk_mul_f32 v[14:15], v[14:15], v[18:19] op_sel_hi:[1,0]
	v_pk_mul_f32 v[12:13], v[12:13], v[18:19] op_sel_hi:[1,0]
	v_pk_mul_f32 v[10:11], v[10:11], v[18:19] op_sel_hi:[1,0]
	v_pk_mul_f32 v[8:9], v[8:9], v[18:19] op_sel_hi:[1,0]
	v_pk_mul_f32 v[2:3], v[2:3], v[18:19] op_sel_hi:[1,0]
	v_pk_mul_f32 v[0:1], v[0:1], v[18:19] op_sel_hi:[1,0]
	v_pk_mul_f32 v[6:7], v[6:7], v[18:19] op_sel_hi:[1,0]
	v_pk_mul_f32 v[4:5], v[4:5], v[18:19] op_sel_hi:[1,0]
	v_max_f32_e32 v12, 0, v12
	v_max_f32_e32 v8, 0, v8
	v_max_f32_e32 v13, 0, v13
	v_max_f32_e32 v9, 0, v9
	v_max_f32_e32 v14, 0, v14
	v_max_f32_e32 v10, 0, v10
	v_max_f32_e32 v15, 0, v15
	v_max_f32_e32 v11, 0, v11
	v_max_f32_e32 v0, 0, v0
	v_max_f32_e32 v1, 0, v1
	v_max_f32_e32 v2, 0, v2
	v_max_f32_e32 v3, 0, v3
	v_max_f32_e32 v4, 0, v4
	v_max_f32_e32 v5, 0, v5
	v_max_f32_e32 v6, 0, v6
	v_max_f32_e32 v7, 0, v7
	v_mul_f32_e32 v12, v12, v12
	v_mul_f32_e32 v8, v8, v8
	v_mul_f32_e32 v13, v13, v13
	v_mul_f32_e32 v9, v9, v9
	v_mul_f32_e32 v14, v14, v14
	v_mul_f32_e32 v10, v10, v10
	v_mul_f32_e32 v15, v15, v15
	v_mul_f32_e32 v11, v11, v11
	v_mul_f32_e32 v18, v0, v0
	v_mul_f32_e32 v19, v1, v1
	v_mul_f32_e32 v22, v2, v2
	v_mul_f32_e32 v23, v3, v3
	v_cvt_pk_bf16_f32 v0, v12, v13
	v_cvt_pk_bf16_f32 v1, v14, v15
	v_cvt_pk_bf16_f32 v2, v8, v9
	v_cvt_pk_bf16_f32 v3, v10, v11
	v_mul_f32_e32 v4, v4, v4
	v_mul_f32_e32 v5, v5, v5
	v_mul_f32_e32 v6, v6, v6
	v_mul_f32_e32 v7, v7, v7
	global_store_dwordx4 v[20:21], v[0:3], off
	s_nop 1
	v_cvt_pk_bf16_f32 v0, v4, v5
	v_cvt_pk_bf16_f32 v1, v6, v7
	v_cvt_pk_bf16_f32 v2, v18, v19
	v_cvt_pk_bf16_f32 v3, v22, v23
	global_store_dwordx4 v[16:17], v[0:3], off offset:256
	s_cbranch_vccnz .LBB0_820
	s_andn2_b64 vcc, exec, s[10:11]
	s_cbranch_vccnz .LBB0_819
	s_barrier
	s_branch .LBB0_819

; #define EPI_LOOP_ROWS _Pragma("unroll") for (int ai = 0; ai < 2; ++ai) _Pragma("unroll") for (int m = 0; m < 4; ++m)
; #define EPI_LOOP_BJ _Pragma("unroll") for (int bj = 0; bj < 2; ++bj)
;     __device__ __forceinline__ void fused(f32x4 (&acc)[2][2][4][2], const Unit& u, int wr, int wc, int fr, int fq, PG8_LAS unsigned char* lds, int wid, int lane) const {
;     ...
;         EPI_LOOP_ROWS { const int row = row0 + ai * HALF + m * 16; const size_t off = (size_t)row * 2048 + col0;
;             const float t = __uint_as_float(__hip_atomic_load((unsigned*)(ss_out + row), __ATOMIC_RELAXED, __HIP_MEMORY_SCOPE_AGENT)); const float rs = 1.f / sqrtf(t * (1.f / 2048.f) + 1e-6f);
;             EPI_LOOP_BJ { const f32x4 ga = *(const f32x4*)(fg + col0 + bj * HALF), gb = *(const f32x4*)(fg + col0 + bj * HALF + 4);
;                 *(f32x4*)(out + off + bj * HALF) = acc[ai][bj][m][0] * rs * ga; *(f32x4*)(out + off + bj * HALF + 4) = acc[ai][bj][m][1] * rs * gb; } }
.LBB0_1052:
	s_or_b64 exec, exec, s[0:1]
	s_barrier
	global_load_dword v154, v[134:135], off sc1
	v_lshl_add_u64 v[114:115], v[114:115], 2, s[8:9]
	global_load_dword v248, v[134:135], off offset:64 sc1
	global_load_dword v249, v[134:135], off offset:128 sc1
	global_load_dword v250, v[134:135], off offset:192 sc1
	global_load_dword v251, v[134:135], off offset:512 sc1
	global_load_dword v252, v[134:135], off offset:576 sc1
	global_load_dword v253, v[134:135], off offset:640 sc1
	global_load_dword v254, v[134:135], off offset:704 sc1
	global_load_dwordx4 v[232:235], v[114:115], off
	global_load_dwordx4 v[236:239], v[114:115], off offset:16
	global_load_dwordx4 v[240:243], v[114:115], off offset:512
	global_load_dwordx4 v[244:247], v[114:115], off offset:528
	v_mov_b32_e32 v155, 0x358637bd
	s_mov_b32 s3, 0xf800000
	v_lshl_add_u64 v[112:113], v[112:113], 2, s[10:11]
	v_lshl_add_u64 v[132:133], v[132:133], 2, s[4:5]
	v_lshl_add_u64 v[96:97], v[96:97], 2, s[10:11]
	v_lshl_add_u64 v[80:81], v[80:81], 2, s[10:11]
	v_lshl_add_u64 v[64:65], v[64:65], 2, s[10:11]
	v_lshl_add_u64 v[48:49], v[48:49], 2, s[10:11]
	v_lshl_add_u64 v[32:33], v[32:33], 2, s[10:11]
	v_lshl_add_u64 v[16:17], v[16:17], 2, s[10:11]
	s_waitcnt vmcnt(0)
	v_mov_b64_e32 v[156:157], v[232:233]
	v_mov_b64_e32 v[158:159], v[234:235]
	v_mov_b64_e32 v[160:161], v[236:237]
	v_mov_b64_e32 v[162:163], v[238:239]
	v_fmamk_f32 v154, v154, 0x3a000000, v155
	v_mul_f32_e32 v164, 0x4f800000, v154
	v_cmp_gt_f32_e32 vcc, s3, v154
	s_nop 1
	v_cndmask_b32_e32 v164, v154, v164, vcc
	v_sqrt_f32_e32 v165, v164
	v_mov_b32_e32 v154, 0x260
	v_add_u32_e32 v166, -1, v165
	v_add_u32_e32 v167, 1, v165
	v_fma_f32 v168, -v166, v165, v164
	v_fma_f32 v169, -v167, v165, v164
	v_cmp_ge_f32_e64 s[0:1], 0, v168
	s_nop 1
	v_cndmask_b32_e64 v165, v165, v166, s[0:1]
	v_cmp_lt_f32_e64 s[0:1], 0, v169
	s_nop 1
	v_cndmask_b32_e64 v165, v165, v167, s[0:1]
	v_mul_f32_e32 v166, 0x37800000, v165
	v_cndmask_b32_e32 v165, v165, v166, vcc
	v_cmp_class_f32_e32 vcc, v164, v154
	s_nop 1
	v_cndmask_b32_e32 v164, v165, v164, vcc
	v_div_scale_f32 v165, s[0:1], v164, v164, 1.0
	v_rcp_f32_e32 v166, v165
	v_div_scale_f32 v167, vcc, 1.0, v164, 1.0
	v_fma_f32 v168, -v165, v166, 1.0
	v_fmac_f32_e32 v166, v168, v166
	v_mul_f32_e32 v168, v167, v166
	v_fma_f32 v169, -v165, v168, v167
	v_fmac_f32_e32 v168, v169, v166
	v_fma_f32 v165, -v165, v168, v167
	v_div_fmas_f32 v165, v165, v166, v168
	v_div_fixup_f32 v164, v165, v164, 1.0
	v_pk_mul_f32 v[124:125], v[124:125], v[164:165] op_sel_hi:[1,0]
	v_pk_mul_f32 v[122:123], v[122:123], v[164:165] op_sel_hi:[1,0]
	v_pk_mul_f32 v[166:167], v[120:121], v[164:165] op_sel_hi:[1,0]
	v_pk_mul_f32 v[168:169], v[118:119], v[164:165] op_sel_hi:[1,0]
	v_pk_mul_f32 v[120:121], v[158:159], v[122:123]
	v_pk_mul_f32 v[118:119], v[156:157], v[124:125]
	v_pk_mul_f32 v[124:125], v[162:163], v[168:169]
	v_pk_mul_f32 v[122:123], v[160:161], v[166:167]
	global_store_dwordx4 v[112:113], v[118:121], off
	global_store_dwordx4 v[112:113], v[122:125], off offset:16
	s_nop 1
	v_mov_b64_e32 v[118:119], v[240:241]
	v_mov_b64_e32 v[120:121], v[242:243]
	s_nop 0
	v_mov_b64_e32 v[122:123], v[244:245]
	v_mov_b64_e32 v[124:125], v[246:247]
	v_pk_mul_f32 v[136:137], v[136:137], v[164:165] op_sel_hi:[1,0]
	v_pk_mul_f32 v[128:129], v[128:129], v[164:165] op_sel_hi:[1,0]
	v_pk_mul_f32 v[130:131], v[130:131], v[164:165] op_sel_hi:[1,0]
	v_pk_mul_f32 v[126:127], v[126:127], v[164:165] op_sel_hi:[1,0]
	v_pk_mul_f32 v[118:119], v[118:119], v[128:129]
	v_pk_mul_f32 v[120:121], v[120:121], v[136:137]
	v_pk_mul_f32 v[122:123], v[122:123], v[126:127]
	v_pk_mul_f32 v[124:125], v[124:125], v[130:131]
	global_store_dwordx4 v[112:113], v[118:121], off offset:512
	global_store_dwordx4 v[112:113], v[122:125], off offset:528
	s_nop 1
	v_mov_b32_e32 v112, v248
	s_nop 0
	v_mov_b64_e32 v[118:119], v[232:233]
	v_mov_b64_e32 v[120:121], v[234:235]
	v_mov_b64_e32 v[122:123], v[236:237]
	v_mov_b64_e32 v[124:125], v[238:239]
	v_fmamk_f32 v112, v112, 0x3a000000, v155
	v_mul_f32_e32 v113, 0x4f800000, v112
	v_cmp_gt_f32_e32 vcc, s3, v112
	s_nop 1
	v_cndmask_b32_e32 v112, v112, v113, vcc
	v_sqrt_f32_e32 v113, v112
	s_nop 0
	v_add_u32_e32 v126, -1, v113
	v_add_u32_e32 v127, 1, v113
	v_fma_f32 v128, -v126, v113, v112
	v_fma_f32 v129, -v127, v113, v112
	v_cmp_ge_f32_e64 s[0:1], 0, v128
	s_nop 1
	v_cndmask_b32_e64 v113, v113, v126, s[0:1]
	v_cmp_lt_f32_e64 s[0:1], 0, v129
	s_nop 1
	v_cndmask_b32_e64 v113, v113, v127, s[0:1]
	v_mul_f32_e32 v126, 0x37800000, v113
	v_cndmask_b32_e32 v113, v113, v126, vcc
	v_cmp_class_f32_e32 vcc, v112, v154
	s_nop 1
	v_cndmask_b32_e32 v126, v113, v112, vcc
	v_div_scale_f32 v127, s[0:1], v126, v126, 1.0
	v_rcp_f32_e32 v128, v127
	v_lshl_add_u64 v[112:113], v[116:117], 2, s[10:11]
	v_div_scale_f32 v116, vcc, 1.0, v126, 1.0
	v_fma_f32 v117, -v127, v128, 1.0
	v_fmac_f32_e32 v128, v117, v128
	v_mul_f32_e32 v117, v116, v128
	v_fma_f32 v129, -v127, v117, v116
	v_fmac_f32_e32 v117, v129, v128
	v_fma_f32 v116, -v127, v117, v116
	v_div_fmas_f32 v116, v116, v128, v117
	v_div_fixup_f32 v116, v116, v126, 1.0
	v_pk_mul_f32 v[110:111], v[110:111], v[116:117] op_sel_hi:[1,0]
	v_pk_mul_f32 v[108:109], v[108:109], v[116:117] op_sel_hi:[1,0]
	v_pk_mul_f32 v[126:127], v[106:107], v[116:117] op_sel_hi:[1,0]
	v_pk_mul_f32 v[128:129], v[104:105], v[116:117] op_sel_hi:[1,0]
	v_pk_mul_f32 v[106:107], v[120:121], v[108:109]
	v_pk_mul_f32 v[104:105], v[118:119], v[110:111]
	v_pk_mul_f32 v[110:111], v[124:125], v[128:129]
	v_pk_mul_f32 v[108:109], v[122:123], v[126:127]
	global_store_dwordx4 v[112:113], v[104:107], off
	global_store_dwordx4 v[112:113], v[108:111], off offset:16
; #define EPI_LOOP_ROWS _Pragma("unroll") for (int ai = 0; ai < 2; ++ai) _Pragma("unroll") for (int m = 0; m < 4; ++m)
; #define EPI_LOOP_BJ _Pragma("unroll") for (int bj = 0; bj < 2; ++bj)
;     __device__ __forceinline__ void fused(f32x4 (&acc)[2][2][4][2], const Unit& u, int wr, int wc, int fr, int fq, PG8_LAS unsigned char* lds, int wid, int lane) const {
;     ...
;         EPI_LOOP_ROWS { const int row = row0 + ai * HALF + m * 16; const size_t off = (size_t)row * 2048 + col0;
;             const float t = __uint_as_float(__hip_atomic_load((unsigned*)(ss_out + row), __ATOMIC_RELAXED, __HIP_MEMORY_SCOPE_AGENT)); const float rs = 1.f / sqrtf(t * (1.f / 2048.f) + 1e-6f);
;             EPI_LOOP_BJ { const f32x4 ga = *(const f32x4*)(fg + col0 + bj * HALF), gb = *(const f32x4*)(fg + col0 + bj * HALF + 4);
;                 *(f32x4*)(out + off + bj * HALF) = acc[ai][bj][m][0] * rs * ga; *(f32x4*)(out + off + bj * HALF + 4) = acc[ai][bj][m][1] * rs * gb; } }
	s_nop 1
	v_mov_b64_e32 v[104:105], v[240:241]
	v_mov_b64_e32 v[106:107], v[242:243]
	s_nop 0
	v_mov_b64_e32 v[108:109], v[244:245]
	v_mov_b64_e32 v[110:111], v[246:247]
	v_pk_mul_f32 v[120:121], v[140:141], v[116:117] op_sel_hi:[1,0]
	v_pk_mul_f32 v[100:101], v[100:101], v[116:117] op_sel_hi:[1,0]
	v_pk_mul_f32 v[122:123], v[102:103], v[116:117] op_sel_hi:[1,0]
	v_pk_mul_f32 v[102:103], v[98:99], v[116:117] op_sel_hi:[1,0]
	v_lshl_add_u64 v[118:119], v[138:139], 2, s[4:5]
	v_pk_mul_f32 v[98:99], v[104:105], v[100:101]
	v_pk_mul_f32 v[100:101], v[106:107], v[120:121]
	v_pk_mul_f32 v[102:103], v[108:109], v[102:103]
	v_pk_mul_f32 v[104:105], v[110:111], v[122:123]
	global_store_dwordx4 v[112:113], v[98:101], off offset:512
	global_store_dwordx4 v[112:113], v[102:105], off offset:528
	s_nop 1
	v_mov_b32_e32 v106, v249
	s_nop 0
	v_mov_b64_e32 v[98:99], v[232:233]
	v_mov_b64_e32 v[100:101], v[234:235]
	v_mov_b64_e32 v[102:103], v[236:237]
	v_mov_b64_e32 v[104:105], v[238:239]
	v_fmamk_f32 v106, v106, 0x3a000000, v155
	v_mul_f32_e32 v107, 0x4f800000, v106
	v_cmp_gt_f32_e32 vcc, s3, v106
	s_nop 1
	v_cndmask_b32_e32 v106, v106, v107, vcc
	v_sqrt_f32_e32 v107, v106
	s_nop 0
	v_add_u32_e32 v108, -1, v107
	v_add_u32_e32 v109, 1, v107
	v_fma_f32 v110, -v108, v107, v106
	v_fma_f32 v111, -v109, v107, v106
	v_cmp_ge_f32_e64 s[0:1], 0, v110
	s_nop 1
	v_cndmask_b32_e64 v107, v107, v108, s[0:1]
	v_cmp_lt_f32_e64 s[0:1], 0, v111
	s_nop 1
	v_cndmask_b32_e64 v107, v107, v109, s[0:1]
	v_mul_f32_e32 v108, 0x37800000, v107
	v_cndmask_b32_e32 v107, v107, v108, vcc
	v_cmp_class_f32_e32 vcc, v106, v154
	s_nop 1
	v_cndmask_b32_e32 v106, v107, v106, vcc
	v_div_scale_f32 v107, s[0:1], v106, v106, 1.0
	v_rcp_f32_e32 v108, v107
	v_div_scale_f32 v109, vcc, 1.0, v106, 1.0
	v_fma_f32 v110, -v107, v108, 1.0
	v_fmac_f32_e32 v108, v110, v108
	v_mul_f32_e32 v110, v109, v108
	v_fma_f32 v111, -v107, v110, v109
	v_fmac_f32_e32 v110, v111, v108
	v_fma_f32 v107, -v107, v110, v109
	v_div_fmas_f32 v107, v107, v108, v110
	v_div_fixup_f32 v106, v107, v106, 1.0
	v_pk_mul_f32 v[94:95], v[94:95], v[106:107] op_sel_hi:[1,0]
	v_pk_mul_f32 v[92:93], v[92:93], v[106:107] op_sel_hi:[1,0]
	v_pk_mul_f32 v[108:109], v[90:91], v[106:107] op_sel_hi:[1,0]
	v_pk_mul_f32 v[110:111], v[88:89], v[106:107] op_sel_hi:[1,0]
	v_pk_mul_f32 v[90:91], v[100:101], v[92:93]
	v_pk_mul_f32 v[88:89], v[98:99], v[94:95]
	v_pk_mul_f32 v[94:95], v[104:105], v[110:111]
	v_pk_mul_f32 v[92:93], v[102:103], v[108:109]
	global_store_dwordx4 v[96:97], v[88:91], off
	global_store_dwordx4 v[96:97], v[92:95], off offset:16
	s_nop 1
	v_mov_b64_e32 v[88:89], v[240:241]
	v_mov_b64_e32 v[90:91], v[242:243]
	s_nop 0
	v_mov_b64_e32 v[92:93], v[244:245]
	v_mov_b64_e32 v[94:95], v[246:247]
	v_pk_mul_f32 v[100:101], v[146:147], v[106:107] op_sel_hi:[1,0]
	v_pk_mul_f32 v[84:85], v[84:85], v[106:107] op_sel_hi:[1,0]
	v_pk_mul_f32 v[102:103], v[86:87], v[106:107] op_sel_hi:[1,0]
	v_pk_mul_f32 v[86:87], v[82:83], v[106:107] op_sel_hi:[1,0]
	v_lshl_add_u64 v[98:99], v[142:143], 2, s[4:5]
	v_pk_mul_f32 v[82:83], v[88:89], v[84:85]
	v_pk_mul_f32 v[84:85], v[90:91], v[100:101]
	v_pk_mul_f32 v[86:87], v[92:93], v[86:87]
	v_pk_mul_f32 v[88:89], v[94:95], v[102:103]
	global_store_dwordx4 v[96:97], v[82:85], off offset:512
	global_store_dwordx4 v[96:97], v[86:89], off offset:528
	s_nop 1
	v_mov_b32_e32 v90, v250
	s_nop 0
	v_mov_b64_e32 v[82:83], v[232:233]
	v_mov_b64_e32 v[84:85], v[234:235]
	v_mov_b64_e32 v[86:87], v[236:237]
	v_mov_b64_e32 v[88:89], v[238:239]
	v_fmamk_f32 v90, v90, 0x3a000000, v155
	v_mul_f32_e32 v91, 0x4f800000, v90
	v_cmp_gt_f32_e32 vcc, s3, v90
	s_nop 1
	v_cndmask_b32_e32 v90, v90, v91, vcc
	v_sqrt_f32_e32 v91, v90
	s_nop 0
	v_add_u32_e32 v92, -1, v91
	v_add_u32_e32 v93, 1, v91
	v_fma_f32 v94, -v92, v91, v90
	v_fma_f32 v95, -v93, v91, v90
	v_cmp_ge_f32_e64 s[0:1], 0, v94
	s_nop 1
	v_cndmask_b32_e64 v91, v91, v92, s[0:1]
	v_cmp_lt_f32_e64 s[0:1], 0, v95
	s_nop 1
	v_cndmask_b32_e64 v91, v91, v93, s[0:1]
	v_mul_f32_e32 v92, 0x37800000, v91
	v_cndmask_b32_e32 v91, v91, v92, vcc
	v_cmp_class_f32_e32 vcc, v90, v154
	s_nop 1
	v_cndmask_b32_e32 v90, v91, v90, vcc
	v_div_scale_f32 v91, s[0:1], v90, v90, 1.0
	v_rcp_f32_e32 v92, v91
	v_div_scale_f32 v93, vcc, 1.0, v90, 1.0
	v_fma_f32 v94, -v91, v92, 1.0
	v_fmac_f32_e32 v92, v94, v92
	v_mul_f32_e32 v94, v93, v92
	v_fma_f32 v95, -v91, v94, v93
	v_fmac_f32_e32 v94, v95, v92
	v_fma_f32 v91, -v91, v94, v93
	v_div_fmas_f32 v91, v91, v92, v94
	v_div_fixup_f32 v90, v91, v90, 1.0
	v_pk_mul_f32 v[78:79], v[78:79], v[90:91] op_sel_hi:[1,0]
	v_pk_mul_f32 v[76:77], v[76:77], v[90:91] op_sel_hi:[1,0]
	v_pk_mul_f32 v[92:93], v[74:75], v[90:91] op_sel_hi:[1,0]
	v_pk_mul_f32 v[94:95], v[72:73], v[90:91] op_sel_hi:[1,0]
	v_pk_mul_f32 v[74:75], v[84:85], v[76:77]
	v_pk_mul_f32 v[72:73], v[82:83], v[78:79]
	v_pk_mul_f32 v[78:79], v[88:89], v[94:95]
	v_pk_mul_f32 v[76:77], v[86:87], v[92:93]
	global_store_dwordx4 v[80:81], v[72:75], off
	global_store_dwordx4 v[80:81], v[76:79], off offset:16
	s_nop 1
	v_mov_b64_e32 v[72:73], v[240:241]
	v_mov_b64_e32 v[74:75], v[242:243]
	s_nop 0
	v_mov_b64_e32 v[76:77], v[244:245]
	v_mov_b64_e32 v[78:79], v[246:247]
	v_pk_mul_f32 v[82:83], v[148:149], v[90:91] op_sel_hi:[1,0]
	v_pk_mul_f32 v[70:71], v[70:71], v[90:91] op_sel_hi:[1,0]
	v_pk_mul_f32 v[84:85], v[68:69], v[90:91] op_sel_hi:[1,0]
	v_pk_mul_f32 v[86:87], v[66:67], v[90:91] op_sel_hi:[1,0]
	v_pk_mul_f32 v[66:67], v[72:73], v[70:71]
	v_pk_mul_f32 v[68:69], v[74:75], v[82:83]
	v_pk_mul_f32 v[70:71], v[76:77], v[86:87]
	v_pk_mul_f32 v[72:73], v[78:79], v[84:85]
	global_store_dwordx4 v[80:81], v[66:69], off offset:512
; #define EPI_LOOP_ROWS _Pragma("unroll") for (int ai = 0; ai < 2; ++ai) _Pragma("unroll") for (int m = 0; m < 4; ++m)
; #define EPI_LOOP_BJ _Pragma("unroll") for (int bj = 0; bj < 2; ++bj)
;     __device__ __forceinline__ void fused(f32x4 (&acc)[2][2][4][2], const Unit& u, int wr, int wc, int fr, int fq, PG8_LAS unsigned char* lds, int wid, int lane) const {
;     ...
;         EPI_LOOP_ROWS { const int row = row0 + ai * HALF + m * 16; const size_t off = (size_t)row * 2048 + col0;
;             const float t = __uint_as_float(__hip_atomic_load((unsigned*)(ss_out + row), __ATOMIC_RELAXED, __HIP_MEMORY_SCOPE_AGENT)); const float rs = 1.f / sqrtf(t * (1.f / 2048.f) + 1e-6f);
;             EPI_LOOP_BJ { const f32x4 ga = *(const f32x4*)(fg + col0 + bj * HALF), gb = *(const f32x4*)(fg + col0 + bj * HALF + 4);
;                 *(f32x4*)(out + off + bj * HALF) = acc[ai][bj][m][0] * rs * ga; *(f32x4*)(out + off + bj * HALF + 4) = acc[ai][bj][m][1] * rs * gb; } }
	global_store_dwordx4 v[80:81], v[70:73], off offset:528
	s_nop 1
	v_mov_b32_e32 v74, v251
	s_nop 0
	v_mov_b64_e32 v[66:67], v[232:233]
	v_mov_b64_e32 v[68:69], v[234:235]
	v_mov_b64_e32 v[70:71], v[236:237]
	v_mov_b64_e32 v[72:73], v[238:239]
	v_fmamk_f32 v74, v74, 0x3a000000, v155
	v_mul_f32_e32 v75, 0x4f800000, v74
	v_cmp_gt_f32_e32 vcc, s3, v74
	s_nop 1
	v_cndmask_b32_e32 v74, v74, v75, vcc
	v_sqrt_f32_e32 v75, v74
	s_nop 0
	v_add_u32_e32 v76, -1, v75
	v_add_u32_e32 v77, 1, v75
	v_fma_f32 v78, -v76, v75, v74
	v_fma_f32 v79, -v77, v75, v74
	v_cmp_ge_f32_e64 s[0:1], 0, v78
	s_nop 1
	v_cndmask_b32_e64 v75, v75, v76, s[0:1]
	v_cmp_lt_f32_e64 s[0:1], 0, v79
	s_nop 1
	v_cndmask_b32_e64 v75, v75, v77, s[0:1]
	v_mul_f32_e32 v76, 0x37800000, v75
	v_cndmask_b32_e32 v75, v75, v76, vcc
	v_cmp_class_f32_e32 vcc, v74, v154
	s_nop 1
	v_cndmask_b32_e32 v74, v75, v74, vcc
	v_div_scale_f32 v75, s[0:1], v74, v74, 1.0
	v_rcp_f32_e32 v76, v75
	v_div_scale_f32 v77, vcc, 1.0, v74, 1.0
	v_fma_f32 v78, -v75, v76, 1.0
	v_fmac_f32_e32 v76, v78, v76
	v_mul_f32_e32 v78, v77, v76
	v_fma_f32 v79, -v75, v78, v77
	v_fmac_f32_e32 v78, v79, v76
	v_fma_f32 v75, -v75, v78, v77
	v_div_fmas_f32 v75, v75, v76, v78
	v_div_fixup_f32 v74, v75, v74, 1.0
	v_pk_mul_f32 v[62:63], v[62:63], v[74:75] op_sel_hi:[1,0]
	v_pk_mul_f32 v[60:61], v[60:61], v[74:75] op_sel_hi:[1,0]
	v_pk_mul_f32 v[76:77], v[58:59], v[74:75] op_sel_hi:[1,0]
	v_pk_mul_f32 v[78:79], v[56:57], v[74:75] op_sel_hi:[1,0]
	v_pk_mul_f32 v[58:59], v[68:69], v[60:61]
	v_pk_mul_f32 v[56:57], v[66:67], v[62:63]
	v_pk_mul_f32 v[62:63], v[72:73], v[78:79]
	v_pk_mul_f32 v[60:61], v[70:71], v[76:77]
	global_store_dwordx4 v[64:65], v[56:59], off
	global_store_dwordx4 v[64:65], v[60:63], off offset:16
	s_nop 1
	v_mov_b64_e32 v[56:57], v[240:241]
	v_mov_b64_e32 v[58:59], v[242:243]
	s_nop 0
	v_mov_b64_e32 v[60:61], v[244:245]
	v_mov_b64_e32 v[62:63], v[246:247]
	v_pk_mul_f32 v[66:67], v[150:151], v[74:75] op_sel_hi:[1,0]
	v_pk_mul_f32 v[54:55], v[54:55], v[74:75] op_sel_hi:[1,0]
	v_pk_mul_f32 v[68:69], v[52:53], v[74:75] op_sel_hi:[1,0]
	v_pk_mul_f32 v[70:71], v[50:51], v[74:75] op_sel_hi:[1,0]
	v_pk_mul_f32 v[50:51], v[56:57], v[54:55]
	v_pk_mul_f32 v[52:53], v[58:59], v[66:67]
	v_pk_mul_f32 v[54:55], v[60:61], v[70:71]
	v_pk_mul_f32 v[56:57], v[62:63], v[68:69]
	global_store_dwordx4 v[64:65], v[50:53], off offset:512
	global_store_dwordx4 v[64:65], v[54:57], off offset:528
	s_nop 1
	v_mov_b32_e32 v58, v252
	s_nop 0
	v_mov_b64_e32 v[50:51], v[232:233]
	v_mov_b64_e32 v[52:53], v[234:235]
	v_mov_b64_e32 v[54:55], v[236:237]
	v_mov_b64_e32 v[56:57], v[238:239]
	v_fmamk_f32 v58, v58, 0x3a000000, v155
	v_mul_f32_e32 v59, 0x4f800000, v58
	v_cmp_gt_f32_e32 vcc, s3, v58
	s_nop 1
	v_cndmask_b32_e32 v58, v58, v59, vcc
	v_sqrt_f32_e32 v59, v58
	s_nop 0
	v_add_u32_e32 v60, -1, v59
	v_add_u32_e32 v61, 1, v59
	v_fma_f32 v62, -v60, v59, v58
	v_fma_f32 v63, -v61, v59, v58
	v_cmp_ge_f32_e64 s[0:1], 0, v62
	s_nop 1
	v_cndmask_b32_e64 v59, v59, v60, s[0:1]
	v_cmp_lt_f32_e64 s[0:1], 0, v63
	s_nop 1
	v_cndmask_b32_e64 v59, v59, v61, s[0:1]
	v_mul_f32_e32 v60, 0x37800000, v59
	v_cndmask_b32_e32 v59, v59, v60, vcc
	v_cmp_class_f32_e32 vcc, v58, v154
	s_nop 1
	v_cndmask_b32_e32 v58, v59, v58, vcc
	v_div_scale_f32 v59, s[0:1], v58, v58, 1.0
	v_rcp_f32_e32 v60, v59
	v_div_scale_f32 v61, vcc, 1.0, v58, 1.0
	v_fma_f32 v62, -v59, v60, 1.0
	v_fmac_f32_e32 v60, v62, v60
	v_mul_f32_e32 v62, v61, v60
	v_fma_f32 v63, -v59, v62, v61
	v_fmac_f32_e32 v62, v63, v60
	v_fma_f32 v59, -v59, v62, v61
	v_div_fmas_f32 v59, v59, v60, v62
	v_div_fixup_f32 v58, v59, v58, 1.0
	v_pk_mul_f32 v[46:47], v[46:47], v[58:59] op_sel_hi:[1,0]
	v_pk_mul_f32 v[44:45], v[44:45], v[58:59] op_sel_hi:[1,0]
	v_pk_mul_f32 v[60:61], v[42:43], v[58:59] op_sel_hi:[1,0]
	v_pk_mul_f32 v[62:63], v[40:41], v[58:59] op_sel_hi:[1,0]
	v_pk_mul_f32 v[42:43], v[52:53], v[44:45]
	v_pk_mul_f32 v[40:41], v[50:51], v[46:47]
	v_pk_mul_f32 v[46:47], v[56:57], v[62:63]
	v_pk_mul_f32 v[44:45], v[54:55], v[60:61]
	global_store_dwordx4 v[48:49], v[40:43], off
	global_store_dwordx4 v[48:49], v[44:47], off offset:16
	s_nop 1
	v_mov_b64_e32 v[40:41], v[240:241]
	v_mov_b64_e32 v[42:43], v[242:243]
	s_nop 0
	v_mov_b64_e32 v[44:45], v[244:245]
	v_mov_b64_e32 v[46:47], v[246:247]
	v_pk_mul_f32 v[50:51], v[152:153], v[58:59] op_sel_hi:[1,0]
	v_pk_mul_f32 v[38:39], v[38:39], v[58:59] op_sel_hi:[1,0]
	v_pk_mul_f32 v[52:53], v[36:37], v[58:59] op_sel_hi:[1,0]
	v_pk_mul_f32 v[54:55], v[34:35], v[58:59] op_sel_hi:[1,0]
	v_pk_mul_f32 v[34:35], v[40:41], v[38:39]
	v_pk_mul_f32 v[36:37], v[42:43], v[50:51]
	v_pk_mul_f32 v[38:39], v[44:45], v[54:55]
	v_pk_mul_f32 v[40:41], v[46:47], v[52:53]
	global_store_dwordx4 v[48:49], v[34:37], off offset:512
	global_store_dwordx4 v[48:49], v[38:41], off offset:528
; #define EPI_LOOP_ROWS _Pragma("unroll") for (int ai = 0; ai < 2; ++ai) _Pragma("unroll") for (int m = 0; m < 4; ++m)
; #define EPI_LOOP_BJ _Pragma("unroll") for (int bj = 0; bj < 2; ++bj)
;     __device__ __forceinline__ void fused(f32x4 (&acc)[2][2][4][2], const Unit& u, int wr, int wc, int fr, int fq, PG8_LAS unsigned char* lds, int wid, int lane) const {
;     ...
;         EPI_LOOP_ROWS { const int row = row0 + ai * HALF + m * 16; const size_t off = (size_t)row * 2048 + col0;
;             const float t = __uint_as_float(__hip_atomic_load((unsigned*)(ss_out + row), __ATOMIC_RELAXED, __HIP_MEMORY_SCOPE_AGENT)); const float rs = 1.f / sqrtf(t * (1.f / 2048.f) + 1e-6f);
;             EPI_LOOP_BJ { const f32x4 ga = *(const f32x4*)(fg + col0 + bj * HALF), gb = *(const f32x4*)(fg + col0 + bj * HALF + 4);
;                 *(f32x4*)(out + off + bj * HALF) = acc[ai][bj][m][0] * rs * ga; *(f32x4*)(out + off + bj * HALF + 4) = acc[ai][bj][m][1] * rs * gb; } }
	s_nop 1
	v_mov_b32_e32 v42, v253
	s_nop 0
	v_mov_b64_e32 v[34:35], v[232:233]
	v_mov_b64_e32 v[36:37], v[234:235]
	v_mov_b64_e32 v[38:39], v[236:237]
	v_mov_b64_e32 v[40:41], v[238:239]
	v_fmamk_f32 v42, v42, 0x3a000000, v155
	v_mul_f32_e32 v43, 0x4f800000, v42
	v_cmp_gt_f32_e32 vcc, s3, v42
	s_nop 1
	v_cndmask_b32_e32 v42, v42, v43, vcc
	v_sqrt_f32_e32 v43, v42
	s_nop 0
	v_add_u32_e32 v44, -1, v43
	v_add_u32_e32 v45, 1, v43
	v_fma_f32 v46, -v44, v43, v42
	v_fma_f32 v47, -v45, v43, v42
	v_cmp_ge_f32_e64 s[0:1], 0, v46
	s_nop 1
	v_cndmask_b32_e64 v43, v43, v44, s[0:1]
	v_cmp_lt_f32_e64 s[0:1], 0, v47
	s_nop 1
	v_cndmask_b32_e64 v43, v43, v45, s[0:1]
	v_mul_f32_e32 v44, 0x37800000, v43
	v_cndmask_b32_e32 v43, v43, v44, vcc
	v_cmp_class_f32_e32 vcc, v42, v154
	s_nop 1
	v_cndmask_b32_e32 v42, v43, v42, vcc
	v_div_scale_f32 v43, s[0:1], v42, v42, 1.0
	v_rcp_f32_e32 v44, v43
	v_div_scale_f32 v45, vcc, 1.0, v42, 1.0
	v_fma_f32 v46, -v43, v44, 1.0
	v_fmac_f32_e32 v44, v46, v44
	v_mul_f32_e32 v46, v45, v44
	v_fma_f32 v47, -v43, v46, v45
	v_fmac_f32_e32 v46, v47, v44
	v_fma_f32 v43, -v43, v46, v45
	v_div_fmas_f32 v43, v43, v44, v46
	v_div_fixup_f32 v42, v43, v42, 1.0
	v_pk_mul_f32 v[30:31], v[30:31], v[42:43] op_sel_hi:[1,0]
	v_pk_mul_f32 v[28:29], v[28:29], v[42:43] op_sel_hi:[1,0]
	v_pk_mul_f32 v[44:45], v[26:27], v[42:43] op_sel_hi:[1,0]
	v_pk_mul_f32 v[46:47], v[24:25], v[42:43] op_sel_hi:[1,0]
	v_pk_mul_f32 v[26:27], v[36:37], v[28:29]
	v_pk_mul_f32 v[24:25], v[34:35], v[30:31]
	v_pk_mul_f32 v[30:31], v[40:41], v[46:47]
	v_pk_mul_f32 v[28:29], v[38:39], v[44:45]
	global_store_dwordx4 v[32:33], v[24:27], off
	global_store_dwordx4 v[32:33], v[28:31], off offset:16
	s_nop 1
	v_mov_b64_e32 v[24:25], v[240:241]
	v_mov_b64_e32 v[26:27], v[242:243]
	s_nop 0
	v_mov_b64_e32 v[28:29], v[244:245]
	v_mov_b64_e32 v[30:31], v[246:247]
	v_pk_mul_f32 v[34:35], v[144:145], v[42:43] op_sel_hi:[1,0]
	v_pk_mul_f32 v[22:23], v[22:23], v[42:43] op_sel_hi:[1,0]
	v_pk_mul_f32 v[36:37], v[20:21], v[42:43] op_sel_hi:[1,0]
	v_pk_mul_f32 v[38:39], v[18:19], v[42:43] op_sel_hi:[1,0]
	v_pk_mul_f32 v[18:19], v[24:25], v[22:23]
	v_pk_mul_f32 v[20:21], v[26:27], v[34:35]
	v_pk_mul_f32 v[22:23], v[28:29], v[38:39]
	v_pk_mul_f32 v[24:25], v[30:31], v[36:37]
	global_store_dwordx4 v[32:33], v[18:21], off offset:512
	global_store_dwordx4 v[32:33], v[22:25], off offset:528
	s_nop 1
	v_mov_b32_e32 v26, v254
	s_nop 0
	v_mov_b64_e32 v[18:19], v[232:233]
	v_mov_b64_e32 v[20:21], v[234:235]
	v_mov_b64_e32 v[22:23], v[236:237]
	v_mov_b64_e32 v[24:25], v[238:239]
	v_fmac_f32_e32 v155, 0x3a000000, v26
	v_mul_f32_e32 v26, 0x4f800000, v155
	v_cmp_gt_f32_e32 vcc, s3, v155
	s_nop 1
	v_cndmask_b32_e32 v26, v155, v26, vcc
	v_sqrt_f32_e32 v27, v26
	s_nop 0
	v_add_u32_e32 v28, -1, v27
	v_add_u32_e32 v29, 1, v27
	v_fma_f32 v30, -v28, v27, v26
	v_fma_f32 v31, -v29, v27, v26
	v_cmp_ge_f32_e64 s[0:1], 0, v30
	s_nop 1
	v_cndmask_b32_e64 v27, v27, v28, s[0:1]
	v_cmp_lt_f32_e64 s[0:1], 0, v31
	s_nop 1
	v_cndmask_b32_e64 v27, v27, v29, s[0:1]
	v_mul_f32_e32 v28, 0x37800000, v27
	v_cndmask_b32_e32 v27, v27, v28, vcc
	v_cmp_class_f32_e32 vcc, v26, v154
	s_nop 1
	v_cndmask_b32_e32 v26, v27, v26, vcc
	v_div_scale_f32 v27, s[0:1], v26, v26, 1.0
	v_rcp_f32_e32 v28, v27
	v_div_scale_f32 v29, vcc, 1.0, v26, 1.0
	v_fma_f32 v30, -v27, v28, 1.0
	v_fmac_f32_e32 v28, v30, v28
	v_mul_f32_e32 v30, v29, v28
	v_fma_f32 v31, -v27, v30, v29
	v_fmac_f32_e32 v30, v31, v28
	v_fma_f32 v27, -v27, v30, v29
	v_div_fmas_f32 v27, v27, v28, v30
	v_div_fixup_f32 v26, v27, v26, 1.0
	v_pk_mul_f32 v[14:15], v[14:15], v[26:27] op_sel_hi:[1,0]
	v_pk_mul_f32 v[12:13], v[12:13], v[26:27] op_sel_hi:[1,0]
	v_pk_mul_f32 v[28:29], v[10:11], v[26:27] op_sel_hi:[1,0]
	v_pk_mul_f32 v[30:31], v[8:9], v[26:27] op_sel_hi:[1,0]
	v_pk_mul_f32 v[10:11], v[20:21], v[12:13]
	v_pk_mul_f32 v[8:9], v[18:19], v[14:15]
	v_pk_mul_f32 v[14:15], v[24:25], v[30:31]
	v_pk_mul_f32 v[12:13], v[22:23], v[28:29]
	global_store_dwordx4 v[16:17], v[8:11], off
	global_store_dwordx4 v[16:17], v[12:15], off offset:16
	s_nop 1
	v_mov_b64_e32 v[8:9], v[240:241]
	v_mov_b64_e32 v[10:11], v[242:243]
	s_nop 0
	v_mov_b64_e32 v[12:13], v[244:245]
	v_mov_b64_e32 v[14:15], v[246:247]
	v_pk_mul_f32 v[18:19], v[0:1], v[26:27] op_sel_hi:[1,0]
	v_pk_mul_f32 v[0:1], v[4:5], v[26:27] op_sel_hi:[1,0]
	v_pk_mul_f32 v[20:21], v[2:3], v[26:27] op_sel_hi:[1,0]
	v_pk_mul_f32 v[4:5], v[6:7], v[26:27] op_sel_hi:[1,0]
	v_pk_mul_f32 v[0:1], v[8:9], v[0:1]
	v_pk_mul_f32 v[2:3], v[10:11], v[18:19]
	v_pk_mul_f32 v[4:5], v[12:13], v[4:5]
	v_pk_mul_f32 v[6:7], v[14:15], v[20:21]
	global_store_dwordx4 v[16:17], v[0:3], off offset:512
	global_store_dwordx4 v[16:17], v[4:7], off offset:528
	s_nop 1
	s_and_saveexec_b64 s[0:1], s[14:15]
	s_cbranch_execz .LBB0_997
